# work-queue pop prefetch: next unit index claimed at the start of the prompt-attention epilogue / G3 unit (hides the atomic round trip), on top of v33
# baseline (speedup 1.0000x reference)
; #define LAS __attribute__((address_space(3)))
; __global__ void __launch_bounds__(NWAVES * 64, 2) hymba_fwd(Args args) {
;     ...
;         bool g2ok = false, g1sok = false;
;         att::attn_setup(F.lds + RING_OFF, inp(F, 9) + (size_t)l * 256, l);
;     ...
;         for (int rep = 0; rep < 2; ++rep)
;     ...
;         const int rep = 0;
;     ...
;         for (int it = 0;; ++it) {
;             if (it == 0) __syncthreads();
;             volatile LAS int* slot = (volatile LAS int*)(F.lds + MISC_OFF) + 16 + (it & 1);
;             if (threadIdx.x == 0) *slot = (int)__hip_atomic_fetch_add((unsigned*)(CTL_ + CW_QUEUE + 64 * (l + 4 * rep)), 1u, __ATOMIC_RELAXED, __HIP_MEMORY_SCOPE_AGENT);
;             __syncthreads();
;             const int idx = __builtin_amdgcn_readfirstlane(*slot);
.LBB0_464:
	s_or_b64 exec, exec, s[0:1]
	s_lshl_b64 s[0:1], s[96:97], 9
	s_lshl_b32 s4, s96, 6
	v_writelane_b32 v255, s0, 0
	s_mov_b32 s5, s73
	s_mov_b64 s[84:85], 0
	v_writelane_b32 v255, s1, 1
	s_lshl_b64 s[0:1], s[96:97], 7
	v_writelane_b32 v255, s0, 2
	s_mov_b32 s52, 0
	s_waitcnt lgkmcnt(0)
	v_writelane_b32 v255, s1, 3
	s_lshl_b32 s0, s96, 4
	v_writelane_b32 v255, s0, 4
	s_mov_b32 s0, s96
	v_writelane_b32 v255, s0, 5
	s_barrier
	s_nop 0
	v_writelane_b32 v255, s1, 6
	s_lshl_b64 s[0:1], s[96:97], 19
	s_lshl_b64 s[0:1], s[0:1], 2
	v_writelane_b32 v255, s0, 7
	s_mov_b64 s[96:97], 0
	s_nop 0
	v_writelane_b32 v255, s1, 8
	s_mov_b32 s98, 0
	s_branch .LBB0_468

; #define LAS __attribute__((address_space(3)))
; __global__ void __launch_bounds__(NWAVES * 64, 2) hymba_fwd(Args args) {
;     ...
;             volatile LAS int* slot = (volatile LAS int*)(F.lds + MISC_OFF) + 16 + (it & 1);
;             if (threadIdx.x == 0) *slot = (int)__hip_atomic_fetch_add((unsigned*)(CTL_ + CW_QUEUE + 64 * (l + 4 * rep)), 1u, __ATOMIC_RELAXED, __HIP_MEMORY_SCOPE_AGENT);
;             __syncthreads();
;             const int idx = __builtin_amdgcn_readfirstlane(*slot);
;             if (idx >= 128 + 512 + NCHUNK * 4) break;
.LBB0_470:
	s_and_b32 s0, s52, 1
	s_lshl_b32 s0, s0, 2
	s_add_i32 s10, s0, 0
	s_add_i32 s10, s10, 0x20180
	s_and_saveexec_b64 s[0:1], s[38:39]
	s_cbranch_execz .LBB0_474
	v_mov_b32_e32 v3, 0x20258
	s_mov_b64 s[6:7], exec
	v_add_u32_e32 v3, 0, v3
	ds_read_b32 v4, v3
	ds_read_b32 v3, v3 offset:4
	s_waitcnt lgkmcnt(1)
	v_readfirstlane_b32 s11, v4
	s_waitcnt lgkmcnt(0)
	v_readfirstlane_b32 s12, v3
	v_mbcnt_lo_u32_b32 v3, s6, 0
	v_mbcnt_hi_u32_b32 v3, s7, v3
	v_cmp_eq_u32_e32 vcc, 0, v3
	s_and_saveexec_b64 s[8:9], vcc
	s_cbranch_execz .LBB0_473
	s_lshl_b64 s[14:15], s[4:5], 2
	s_add_u32 s14, s11, s14
	s_addc_u32 s15, s12, s15
	s_bcnt1_i32_b64 s6, s[6:7]
	v_mov_b32_e32 v4, s6
	s_cmp_lg_u32 s98, 0
	s_cbranch_scc1 .Lq_have
	global_atomic_add v238, v234, v4, s[14:15] sc0
.Lq_have:
	s_mov_b32 s98, 0
	s_waitcnt vmcnt(0)
	v_mov_b32_e32 v5, v238
.LBB0_473:
	s_or_b64 exec, exec, s[8:9]
	v_readfirstlane_b32 s6, v5
	v_mov_b32_e32 v4, s10
	s_nop 0
	v_add_u32_e32 v3, s6, v3
	ds_write_b32 v4, v3

; #define LAS __attribute__((address_space(3)))
; __device__ __forceinline__ int fresh_tid() { int t = threadIdx.x; asm volatile("" : "+v"(t)); return t; }
; #define CNT_WAIT(w, target) do { if (threadIdx.x == 0) { unsigned* bar_ = (unsigned*)(CTL_ + CW_BAR); XB_SPIN(xb_ld((unsigned*)(w)) < (unsigned)(target), bar_); \
;         __builtin_amdgcn_fence(__ATOMIC_ACQUIRE, "agent"); asm volatile("s_waitcnt vmcnt(0)" ::: "memory"); } __syncthreads(); } while (0)
; #define WSB(off) (wsp(F) + (off))
; __device__ __forceinline__ void g3_unit(LAS float* part, int c, int h, const bf16* ACT, const bf16* OI, const bf16* QT, const bf16* SCT, const float* gnorm  , bf16* MIX) {
;     const int tid = fresh_tid(), wid = __builtin_amdgcn_readfirstlane(tid >> 6), lane = tid & 63, r = lane & 31, hh = lane >> 5;
;     const int jb = wid >> 1, tb = wid & 1; const int row = 64 * c + tb * 32 + r;
;     f32x16 acc = {};
;     const bf16* ap = SCT + ((size_t)(c * 4 + h) * 128 + jb * 32 + r) * 64 + 8 * hh; const bf16* bp = QT + (size_t)row * 256 + h * 64 + 8 * hh;
; #pragma unroll
;     for (int kk = 0; kk < 4; ++kk) acc = __builtin_amdgcn_mfma_f32_32x32x16_bf16(*(const bf16x8*)(ap + kk * 16), *(const bf16x8*)(bp + kk * 16), acc, 0, 0, 0);
;     const int j0 = jb * 32 + 4 * hh;
;     const bf16* oip = OI + (size_t)row * 512 + h * 128 + j0;
;     const bf16* gp = ACT + (size_t)row * NIN + 1280 + h * 128 + j0;
;     v2u ggv[4]; f32x4 gnv[4];
; #pragma unroll
;     for (int q = 0; q < 4; ++q) { ggv[q] = *(const v2u*)(gp + 8 * q); gnv[q] = *(const f32x4*)(gnorm + j0 + 8 * q); }
; __global__ void __launch_bounds__(NWAVES * 64, 2) hymba_fwd(Args args) {
;     ...
;             } else { const int i = idx - 640;
;                 if ((i >> 2) < NPCH) { if (!g2ok) { CNT_WAIT(CTL_ + CW_QUEUE + 64 * l + 16, 256); g2ok = true; } }
;                 else { if (!g1sok) { CNT_WAIT(CTL_ + CW_QUEUE + 64 * l + 32, 64); g1sok = true; } }
;     ...
;                 for (int r3_ = 0; r3_ < 5; ++r3_)
;     ...
;                 gla::g3_unit((LAS float*)(F.lds + RING_OFF + att::OFF_G3), i >> 2, i & 3, ACT_, (const bf16*)WSB(WS_OI), (const bf16*)WSB(WS_QT), (const bf16*)WSB(WS_SC), inp(F, 8) + (size_t)l * 128, MIX_);
.LBB0_516:
.LBB0_517:
	s_and_saveexec_b64 s[8:9], s[38:39]
	s_cbranch_execz .Lpf_skip_g3
	v_mov_b32_e32 v4, 0x20258
	ds_read_b32 v5, v4
	ds_read_b32 v7, v4 offset:4
	s_waitcnt lgkmcnt(0)
	v_readfirstlane_b32 s12, v5
	v_readfirstlane_b32 s13, v7
	s_lshl_b64 s[14:15], s[4:5], 2
	s_add_u32 s12, s12, s14
	s_addc_u32 s13, s13, s15
	v_mov_b32_e32 v4, 1
	s_nop 1
	global_atomic_add v238, v234, v4, s[12:13] sc0
	s_mov_b32 s98, 1
.Lpf_skip_g3:
	s_or_b64 exec, exec, s[8:9]
	v_mov_b32_e32 v3, 0x20258
	v_mov_b32_e32 v6, 0x20200
	v_add_u32_e32 v3, 0, v3
	s_waitcnt vmcnt(4)
	ds_read_b32 v32, v3
	ds_read_b32 v33, v3 offset:4
	v_mov_b32_e32 v3, 0x20258
	s_lshr_b32 s8, s20, 2
	v_add_u32_e32 v3, 0, v3
	ds_read_b32 v16, v3
	ds_read_b32 v17, v3 offset:4
	v_mov_b32_e32 v3, 0x20258
	s_and_b32 s18, s53, 3
	v_add_u32_e32 v3, 0, v3
	ds_read_b32 v4, v3
	ds_read_b32 v3, v3 offset:4
	v_readlane_b32 s14, v255, 0
	v_readlane_b32 s15, v255, 1
	s_waitcnt lgkmcnt(1)
	v_readfirstlane_b32 s12, v4
	v_mov_b32_e32 v4, 0x20258
	s_waitcnt lgkmcnt(0)
	v_readfirstlane_b32 s13, v3
	v_add_u32_e32 v4, 0, v4
	ds_read_b32 v5, v4
	ds_read_b32 v4, v4 offset:4
	v_mov_b32_e32 v3, 0x20258
	v_add_u32_e32 v6, 0, v6
	ds_read_b32 v7, v6
	ds_read_b32 v6, v6 offset:4
	s_waitcnt lgkmcnt(2)
	v_readfirstlane_b32 s17, v4
	v_add_u32_e32 v3, 0, v3
	s_waitcnt lgkmcnt(1)
	v_readfirstlane_b32 s9, v7
	v_mov_b32_e32 v4, v0
	s_waitcnt lgkmcnt(0)
	v_readfirstlane_b32 s11, v6
	s_add_u32 s10, s9, s14
	ds_read_b32 v53, v3
	ds_read_b32 v74, v3 offset:4
	s_addc_u32 s11, s11, s15
	v_readfirstlane_b32 s9, v4
	s_ashr_i32 s15, s9, 6
	s_lshl_b32 s14, s15, 5
	s_lshl_b32 s19, s8, 6
	s_and_b32 s14, s14, 32
	v_and_b32_e32 v3, 31, v4
	s_or_b32 s19, s14, s19
	s_lshl_b32 s8, s8, 9
	s_lshl_b32 s72, s18, 7
	v_or_b32_e32 v196, s19, v3
	s_or_b32 s19, s8, s72
	s_ashr_i32 s8, s9, 2
	s_andn2_b32 s8, s8, 31
	s_ashr_i32 s9, s8, 31
	s_add_u32 s19, s8, s19
	s_addc_u32 s20, s9, 0
	v_readfirstlane_b32 s16, v5
	v_bfe_u32 v52, v4, 5, 1
	v_or_b32_e32 v4, s19, v3
	v_mov_b32_e32 v5, s20
	v_lshlrev_b64 v[4:5], 7, v[4:5]
	v_lshl_add_u64 v[4:5], s[16:17], 0, v[4:5]
	v_lshlrev_b32_e32 v6, 4, v52
	v_mov_b32_e32 v7, v197
	v_lshl_add_u64 v[12:13], v[4:5], 0, v[6:7]
	v_lshlrev_b64 v[4:5], 9, v[196:197]
	v_lshl_add_u64 v[4:5], s[12:13], 0, v[4:5]
	v_lshl_add_u64 v[4:5], v[4:5], 0, s[72:73]
	s_mov_b32 s12, 0x1f100000
	v_lshl_add_u64 v[14:15], v[4:5], 0, v[6:7]
	v_add_co_u32_e32 v4, vcc, s12, v12
	s_mov_b32 s12, 0x23300000
	s_nop 0
	v_addc_co_u32_e32 v5, vcc, 0, v13, vcc
	global_load_dwordx4 v[4:7], v[4:5], off
	v_add_co_u32_e32 v8, vcc, s12, v14
	s_mov_b64 s[12:13], 0x1f100000
	s_nop 0
	v_addc_co_u32_e32 v9, vcc, 0, v15, vcc
	global_load_dwordx4 v[8:11], v[8:9], off
	v_lshl_add_u64 v[12:13], v[12:13], 0, s[12:13]
	global_load_dwordx4 v[20:23], v[12:13], off offset:32
	s_mov_b64 s[16:17], 0x23300000
	v_lshl_add_u64 v[14:15], v[14:15], 0, s[16:17]
	global_load_dwordx4 v[24:27], v[14:15], off offset:32
	global_load_dwordx4 v[54:57], v[12:13], off offset:64
	global_load_dwordx4 v[58:61], v[14:15], off offset:64
	v_readfirstlane_b32 s12, v16
	v_readfirstlane_b32 s13, v17
	v_lshl_or_b32 v16, v52, 2, s8
	v_lshlrev_b64 v[18:19], 10, v[196:197]
	v_ashrrev_i32_e32 v17, 31, v16
	s_lshl_b32 s16, s18, 8
	s_mov_b32 s17, s73
	v_lshl_add_u64 v[18:19], s[12:13], 0, v[18:19]
	s_waitcnt vmcnt(9)
; __device__ __forceinline__ void g3_unit(LAS float* part, int c, int h, const bf16* ACT, const bf16* OI, const bf16* QT, const bf16* SCT, const float* gnorm  , bf16* MIX) {
;     ...
;     const bf16* ap = SCT + ((size_t)(c * 4 + h) * 128 + jb * 32 + r) * 64 + 8 * hh; const bf16* bp = QT + (size_t)row * 256 + h * 64 + 8 * hh;
; #pragma unroll
;     for (int kk = 0; kk < 4; ++kk) acc = __builtin_amdgcn_mfma_f32_32x32x16_bf16(*(const bf16x8*)(ap + kk * 16), *(const bf16x8*)(bp + kk * 16), acc, 0, 0, 0);
;     const int j0 = jb * 32 + 4 * hh;
;     const bf16* oip = OI + (size_t)row * 512 + h * 128 + j0;
;     const bf16* gp = ACT + (size_t)row * NIN + 1280 + h * 128 + j0;
;     v2u ggv[4]; f32x4 gnv[4];
; #pragma unroll
;     for (int q = 0; q < 4; ++q) { ggv[q] = *(const v2u*)(gp + 8 * q); gnv[q] = *(const f32x4*)(gnorm + j0 + 8 * q); }
;     float ss = 0.f;
; #pragma unroll
;     for (int q = 0; q < 4; ++q) { const v2u ow = *(const v2u*)(oip + 8 * q);
;       const float oi[4] = {__builtin_bit_cast(float, ow.x << 16), __builtin_bit_cast(float, ow.x & 0xffff0000u), __builtin_bit_cast(float, ow.y << 16), __builtin_bit_cast(float, ow.y & 0xffff0000u)};
; #pragma unroll
;       for (int e = 0; e < 4; ++e) { acc[4 * q + e] += oi[e]; ss += acc[4 * q + e] * acc[4 * q + e]; } }
;     ss += __shfl_xor(ss, 32);
;     if (hh == 0) part[wid * 32 + r] = ss;
	v_lshlrev_b64 v[28:29], 1, v[16:17]
	v_lshl_add_u64 v[18:19], v[18:19], 0, s[16:17]
	v_lshl_add_u64 v[18:19], v[18:19], 0, v[28:29]
	s_mov_b32 s12, 0x21100000
	v_add_co_u32_e32 v30, vcc, s12, v18
	s_mov_b64 s[12:13], 0x21100000
	s_nop 0
	v_addc_co_u32_e32 v31, vcc, 0, v19, vcc
	global_load_dwordx2 v[38:39], v[30:31], off
	global_load_dwordx4 v[62:65], v[12:13], off offset:96
	v_lshl_add_u64 v[12:13], v[18:19], 0, s[12:13]
	global_load_dwordx2 v[42:43], v[12:13], off offset:16
	global_load_dwordx4 v[66:69], v[14:15], off offset:96
	global_load_dwordx2 v[70:71], v[12:13], off offset:32
	global_load_dwordx2 v[72:73], v[12:13], off offset:48
	v_readfirstlane_b32 s12, v32
	v_readfirstlane_b32 s13, v33
	v_lshl_add_u64 v[46:47], v[16:17], 2, s[10:11]
	v_mov_b32_e32 v12, s12
	v_mov_b32_e32 v13, s13
	v_mad_u64_u32 v[12:13], s[12:13], v196, s90, v[12:13]
	v_lshl_add_u64 v[12:13], v[12:13], 0, s[16:17]
	v_lshl_add_u64 v[28:29], v[12:13], 0, v[28:29]
	s_mov_b64 s[12:13], 0xce00a00
	s_mov_b32 s10, 0xce00000
	v_lshl_add_u64 v[36:37], v[28:29], 0, s[12:13]
	v_add_co_u32_e32 v28, vcc, s10, v28
	s_waitcnt lgkmcnt(1)
	v_readfirstlane_b32 s10, v53
	v_addc_co_u32_e32 v29, vcc, 0, v29, vcc
	global_load_dwordx2 v[48:49], v[28:29], off offset:2560
	global_load_dwordx4 v[32:35], v[46:47], off
	s_nop 0
	global_load_dwordx4 v[28:31], v[46:47], off offset:32
	global_load_dwordx2 v[44:45], v[36:37], off offset:16
	global_load_dwordx2 v[40:41], v[36:37], off offset:32
	s_nop 0
	global_load_dwordx2 v[36:37], v[36:37], off offset:48
	s_waitcnt lgkmcnt(0)
	v_readfirstlane_b32 s11, v74
	s_waitcnt vmcnt(16)
	v_mfma_f32_32x32x16_bf16 v[4:19], v[4:7], v[8:11], 0
	s_waitcnt vmcnt(14)
	v_mfma_f32_32x32x16_bf16 v[4:19], v[20:23], v[24:27], v[4:19]
	global_load_dwordx4 v[24:27], v[46:47], off offset:64
	global_load_dwordx4 v[20:23], v[46:47], off offset:96
	s_waitcnt vmcnt(13)
	v_lshlrev_b32_e32 v46, 16, v38
	v_mfma_f32_32x32x16_bf16 v[4:19], v[54:57], v[58:61], v[4:19]
	v_and_b32_e32 v47, 0xffff0000, v38
	v_lshlrev_b32_e32 v38, 16, v39
	v_and_b32_e32 v39, 0xffff0000, v39
	s_waitcnt vmcnt(11)
	v_lshlrev_b32_e32 v54, 16, v42
	v_and_b32_e32 v55, 0xffff0000, v42
	v_lshlrev_b32_e32 v42, 16, v43
	v_and_b32_e32 v43, 0xffff0000, v43
	s_waitcnt vmcnt(10)
	v_mfma_f32_32x32x16_bf16 v[4:19], v[62:65], v[66:69], v[4:19]
	s_nop 11
	v_pk_add_f32 v[50:51], v[4:5], v[46:47]
	v_pk_add_f32 v[4:5], v[6:7], v[38:39]
	v_pk_add_f32 v[46:47], v[8:9], v[54:55]
	v_pk_mul_f32 v[54:55], v[50:51], v[50:51]
	v_pk_mul_f32 v[56:57], v[4:5], v[4:5]
	v_add_f32_e32 v54, v54, v55
	v_add_f32_e32 v54, v56, v54
	v_pk_mul_f32 v[58:59], v[46:47], v[46:47]
	v_add_f32_e32 v54, v57, v54
	v_pk_add_f32 v[6:7], v[10:11], v[42:43]
	v_add_f32_e32 v54, v58, v54
	v_pk_mul_f32 v[60:61], v[6:7], v[6:7]
	s_waitcnt vmcnt(9)
	v_lshlrev_b32_e32 v8, 16, v70
	v_and_b32_e32 v9, 0xffff0000, v70
	v_add_f32_e32 v54, v59, v54
	v_pk_add_f32 v[42:43], v[12:13], v[8:9]
	v_add_f32_e32 v54, v60, v54
	v_pk_mul_f32 v[12:13], v[42:43], v[42:43]
	v_lshlrev_b32_e32 v8, 16, v71
	v_and_b32_e32 v9, 0xffff0000, v71
	v_add_f32_e32 v54, v61, v54
	v_pk_add_f32 v[38:39], v[14:15], v[8:9]
	v_add_f32_e32 v12, v12, v54
	v_pk_mul_f32 v[14:15], v[38:39], v[38:39]
	s_waitcnt vmcnt(8)
	v_lshlrev_b32_e32 v8, 16, v72
	v_and_b32_e32 v9, 0xffff0000, v72
	v_add_f32_e32 v12, v13, v12
	v_pk_add_f32 v[10:11], v[16:17], v[8:9]
	v_add_f32_e32 v12, v14, v12
	v_pk_mul_f32 v[16:17], v[10:11], v[10:11]
	v_lshlrev_b32_e32 v8, 16, v73
	v_and_b32_e32 v9, 0xffff0000, v73
	v_add_f32_e32 v12, v15, v12
	v_and_b32_e32 v14, 64, v239
	v_pk_add_f32 v[8:9], v[18:19], v[8:9]
	v_add_f32_e32 v12, v16, v12
	v_xor_b32_e32 v13, 32, v239
	v_add_u32_e32 v14, 64, v14
	v_pk_mul_f32 v[18:19], v[8:9], v[8:9]
	v_add_f32_e32 v12, v17, v12
	v_cmp_lt_i32_e32 vcc, v13, v14
	v_add_f32_e32 v12, v18, v12
	v_add_f32_e32 v12, v19, v12
	v_cndmask_b32_e32 v13, v239, v13, vcc
	v_lshlrev_b32_e32 v13, 2, v13
	ds_bpermute_b32 v13, v13, v12
	v_cmp_eq_u32_e32 vcc, 0, v52
	s_and_saveexec_b64 s[12:13], vcc
	s_cbranch_execz .LBB0_519
	s_lshl_b32 s15, s15, 7
	s_add_i32 s15, s15, 0
	s_waitcnt lgkmcnt(0)
	v_add_f32_e32 v12, v12, v13
	v_lshl_add_u32 v13, v3, 2, s15
	v_add_u32_e32 v13, 0x1c900, v13
	ds_write_b32 v13, v12

; #define RESC(a) do { if (__any((a) < 1.f)) { if (hi == 0) al_l[r32] = (a); asm volatile("s_waitcnt lgkmcnt(0)" ::: "memory"); \
;     _Pragma("unroll") for (int d = 0; d < 4; ++d) _Pragma("unroll") for (int r = 0; r < 16; ++r) o[d][r] *= al_l[crow(r, hi)]; \
;     _Pragma("unroll") for (int r = 0; r < 4; ++r) osum[r] *= al_l[4 * (lane >> 4) + r + 16 * (lane & 1)]; } } while (0)
; template <bool SAFE>
; __device__ __forceinline__ bool attn_unit_prompt_t(LAS unsigned char* lds, const bf16* Kg, const bf16* Vg, const bf16* Qrow0, bf16* Orow0, int NT, int qpos0, int h, const float* gnorm) {
;     ...
;   FINISH_PV(pA0, pA1, vrd + VS(NT - 2), pB0, pB1, rmx); PARTIAL(pB0, pB1, alB, false, rmx); RESC(alB);
;   FINISH_PV(pB0, pB1, vrd + VS(NT - 1), pB0, pB1, rmx);
;     ...
;   if (ph == 0) { asm volatile("s_barrier" ::: "memory"); }
;     ...
;   __builtin_amdgcn_s_setprio(0);
.LBB0_595:
	s_lshl_b32 s0, s48, 14
	s_and_b32 s0, s0, 0xc000
	v_exp_f32_e32 v3, v114
	v_add_u32_e32 v114, s0, v194
	ds_read_b64_tr_b16 v[8:9], v114 offset:49152
	ds_read_b64_tr_b16 v[12:13], v114 offset:49664
	ds_read_b64_tr_b16 v[98:99], v114 offset:50176
	ds_read_b64_tr_b16 v[102:103], v114 offset:50688
	ds_read_b64_tr_b16 v[10:11], v114 offset:51200
	ds_read_b64_tr_b16 v[14:15], v114 offset:51712
	ds_read_b64_tr_b16 v[100:101], v114 offset:52224
	ds_read_b64_tr_b16 v[104:105], v114 offset:52736
	v_exp_f32_e32 v107, v117
	v_exp_f32_e32 v108, v118
	v_exp_f32_e32 v109, v119
	v_exp_f32_e32 v16, v115
	v_exp_f32_e32 v17, v116
	v_exp_f32_e32 v110, v120
	v_exp_f32_e32 v111, v121
	v_cvt_pk_bf16_f32 v106, v3, v16
	v_cvt_pk_bf16_f32 v107, v17, v107
	v_cvt_pk_bf16_f32 v108, v108, v109
	v_cvt_pk_bf16_f32 v109, v110, v111
	v_exp_f32_e32 v3, v122
	s_waitcnt lgkmcnt(3)
	v_mfma_f32_32x32x16_bf16 v[66:81], v[106:109], v[8:11], v[66:81]
	v_exp_f32_e32 v16, v123
	v_exp_f32_e32 v17, v124
	v_exp_f32_e32 v115, v125
	v_exp_f32_e32 v116, v126
	v_exp_f32_e32 v117, v127
	v_exp_f32_e32 v118, v128
	v_exp_f32_e32 v119, v129
	s_waitcnt lgkmcnt(2)
	v_mfma_f32_32x32x16_bf16 v[50:65], v[106:109], v[12:15], v[50:65]
	v_exp_f32_e32 v94, v94
	v_exp_f32_e32 v95, v95
	v_exp_f32_e32 v96, v96
	v_exp_f32_e32 v97, v97
	s_waitcnt lgkmcnt(1)
	v_mfma_f32_32x32x16_bf16 v[34:49], v[106:109], v[98:101], v[34:49]
	ds_read_b64_tr_b16 v[8:9], v114 offset:53248
	ds_read_b64_tr_b16 v[12:13], v114 offset:53760
	ds_read_b64_tr_b16 v[98:99], v114 offset:54272
	ds_read_b64_tr_b16 v[110:111], v114 offset:54784
	ds_read_b64_tr_b16 v[10:11], v114 offset:55296
	ds_read_b64_tr_b16 v[14:15], v114 offset:55808
	ds_read_b64_tr_b16 v[100:101], v114 offset:56320
	ds_read_b64_tr_b16 v[112:113], v114 offset:56832
	s_waitcnt lgkmcnt(8)
	v_mfma_f32_32x32x16_bf16 v[18:33], v[106:109], v[102:105], v[18:33]
	v_cvt_pk_bf16_f32 v102, v3, v16
	v_cvt_pk_bf16_f32 v103, v17, v115
	v_cvt_pk_bf16_f32 v104, v116, v117
	v_cvt_pk_bf16_f32 v105, v118, v119
	v_exp_f32_e32 v3, v82
	v_exp_f32_e32 v16, v83
	v_exp_f32_e32 v17, v84
	s_waitcnt lgkmcnt(3)
	v_mfma_f32_32x32x16_bf16 v[66:81], v[102:105], v[8:11], v[66:81]
	v_exp_f32_e32 v115, v85
	v_exp_f32_e32 v116, v86
	v_exp_f32_e32 v117, v89
	s_waitcnt lgkmcnt(2)
	v_mfma_f32_32x32x16_bf16 v[50:65], v[102:105], v[12:15], v[50:65]
	s_waitcnt lgkmcnt(1)
	v_mfma_f32_32x32x16_bf16 v[34:49], v[102:105], v[98:101], v[34:49]
	v_exp_f32_e32 v100, v87
	v_exp_f32_e32 v101, v88
	ds_read_b64_tr_b16 v[8:9], v114 offset:57344
	ds_read_b64_tr_b16 v[12:13], v114 offset:57856
	ds_read_b64_tr_b16 v[82:83], v114 offset:58368
	ds_read_b64_tr_b16 v[86:87], v114 offset:58880
	ds_read_b64_tr_b16 v[10:11], v114 offset:59392
	ds_read_b64_tr_b16 v[14:15], v114 offset:59904
	ds_read_b64_tr_b16 v[84:85], v114 offset:60416
	ds_read_b64_tr_b16 v[88:89], v114 offset:60928
	v_cvt_pk_bf16_f32 v98, v3, v16
	v_cvt_pk_bf16_f32 v99, v17, v115
	v_cvt_pk_bf16_f32 v100, v116, v100
	s_waitcnt lgkmcnt(8)
	v_mfma_f32_32x32x16_bf16 v[18:33], v[102:105], v[110:113], v[18:33]
	v_cvt_pk_bf16_f32 v101, v101, v117
	v_exp_f32_e32 v3, v90
	v_exp_f32_e32 v16, v91
	v_exp_f32_e32 v17, v92
	v_exp_f32_e32 v110, v93
	s_waitcnt lgkmcnt(3)
	v_mfma_f32_32x32x16_bf16 v[66:81], v[98:101], v[8:11], v[66:81]
	s_waitcnt lgkmcnt(2)
	v_mfma_f32_32x32x16_bf16 v[50:65], v[98:101], v[12:15], v[50:65]
	s_waitcnt lgkmcnt(1)
	v_mfma_f32_32x32x16_bf16 v[34:49], v[98:101], v[82:85], v[34:49]
	ds_read_b64_tr_b16 v[8:9], v114 offset:61440
	ds_read_b64_tr_b16 v[12:13], v114 offset:61952
	ds_read_b64_tr_b16 v[82:83], v114 offset:62464
	ds_read_b64_tr_b16 v[90:91], v114 offset:62976
	ds_read_b64_tr_b16 v[10:11], v114 offset:63488
	ds_read_b64_tr_b16 v[14:15], v114 offset:64000
	ds_read_b64_tr_b16 v[84:85], v114 offset:64512
	ds_read_b64_tr_b16 v[92:93], v114 offset:65024
	s_waitcnt lgkmcnt(8)
	v_mfma_f32_32x32x16_bf16 v[18:33], v[98:101], v[86:89], v[18:33]
	v_cvt_pk_bf16_f32 v86, v3, v16
	v_cvt_pk_bf16_f32 v87, v17, v110
	v_cvt_pk_bf16_f32 v88, v94, v95
	v_cvt_pk_bf16_f32 v89, v96, v97
	v_mfma_f32_16x16x32_bf16 v[4:7], v[106:109], v[162:165], v[4:7]
	v_mfma_f32_16x16x32_bf16 v[4:7], v[102:105], v[162:165], v[4:7]
	s_waitcnt lgkmcnt(3)
	v_mfma_f32_32x32x16_bf16 v[66:81], v[86:89], v[8:11], v[66:81]
	s_waitcnt lgkmcnt(2)
	v_mfma_f32_32x32x16_bf16 v[50:65], v[86:89], v[12:15], v[50:65]
	s_waitcnt lgkmcnt(1)
	v_mfma_f32_32x32x16_bf16 v[34:49], v[86:89], v[82:85], v[34:49]
	v_mfma_f32_16x16x32_bf16 v[4:7], v[98:101], v[162:165], v[4:7]
	s_waitcnt lgkmcnt(0)
	v_mfma_f32_32x32x16_bf16 v[18:33], v[86:89], v[90:93], v[18:33]
	v_mfma_f32_16x16x32_bf16 v[4:7], v[86:89], v[162:165], v[4:7]
	s_setprio 0
	s_and_saveexec_b64 s[6:7], s[38:39]
	s_cbranch_execz .Lpf_skip_pa
	v_mov_b32_e32 v8, 0x20258
	ds_read_b32 v9, v8
	ds_read_b32 v10, v8 offset:4
	s_waitcnt lgkmcnt(0)
	v_readfirstlane_b32 s12, v9
	v_readfirstlane_b32 s13, v10
	s_lshl_b64 s[14:15], s[4:5], 2
	s_add_u32 s12, s12, s14
	s_addc_u32 s13, s13, s15
	v_mov_b32_e32 v8, 1
	s_nop 1
	global_atomic_add v238, v234, v8, s[12:13] sc0
	s_mov_b32 s98, 1
; #define LAS __attribute__((address_space(3)))
; __device__ __forceinline__ int crow(int r, int hi) { return (r & 3) + 8 * (r >> 2) + 4 * hi; }
; __device__ __forceinline__ int crow(int r, int hi) { return (r & 3) + 8 * (r >> 2) + 4 * hi; }
; __device__ __forceinline__ int crow(int r, int hi) { return (r & 3) + 8 * (r >> 2) + 4 * hi; }
; template <bool SAFE>
; __device__ __forceinline__ bool attn_unit_prompt_t(LAS unsigned char* lds, const bf16* Kg, const bf16* Vg, const bf16* Qrow0, bf16* Orow0, int NT, int qpos0, int h, const float* gnorm) {
;     ...
;   __builtin_amdgcn_s_setprio(0);
;   float rli[16];
;   if ((lane & 15) < 2) {
; #pragma unroll
;     for (int r = 0; r < 4; ++r) li_l[4 * (lane >> 4) + r + 16 * (lane & 15)] = osum[r]; }
; #pragma unroll
;   for (int r = 0; r < 16; ++r) rli[r] = __builtin_amdgcn_rcpf(li_l[crow(r, hi)]);
;   bool bad = false;
;   if (!SAFE) {
; #pragma unroll
;     for (int r = 0; r < 4; ++r) bad |= !(osum[r] < 3e38f); }
;   __syncthreads();
;   LAS float* X = (LAS float*)lds + rb * 4096 + lane;
;   if (g == 1) {
; #pragma unroll
;     for (int r = 0; r < 16; ++r)
; #pragma unroll
;       for (int d0 = 0; d0 < 4; ++d0) X[(r * 4 + d0) * 64] = o[d0][r] * rli[r];
;   }
.Lpf_skip_pa:
	s_or_b64 exec, exec, s[6:7]
	v_cmp_lt_u32_e32 vcc, 1, v224
	s_and_saveexec_b64 s[0:1], vcc
	s_xor_b64 s[0:1], exec, s[0:1]
	s_andn2_saveexec_b64 s[0:1], s[0:1]
	v_lshlrev_b32_e32 v3, 6, v224
	v_add3_u32 v3, s27, v193, v3
	s_nop 0
	ds_write_b128 v3, v[4:7]
	s_or_b64 exec, exec, s[0:1]
	v_lshl_add_u32 v3, v191, 4, s27
	ds_read_b128 v[8:11], v3
	ds_read_b128 v[84:87], v3 offset:32
	s_lshl_b32 s0, s25, 14
	s_add_i32 s0, s0, 0
	s_cmp_lg_u32 s24, 1
	s_waitcnt lgkmcnt(1)
	v_rcp_f32_e32 v12, v8
	v_rcp_f32_e32 v13, v9
	v_rcp_f32_e32 v16, v10
	v_rcp_f32_e32 v17, v11
	ds_read_b128 v[8:11], v3 offset:64
	ds_read_b128 v[96:99], v3 offset:96
	s_waitcnt lgkmcnt(2)
	v_rcp_f32_e32 v84, v84
	v_rcp_f32_e32 v85, v85
	v_rcp_f32_e32 v88, v86
	v_rcp_f32_e32 v89, v87
	s_waitcnt lgkmcnt(1)
	v_rcp_f32_e32 v90, v8
	v_rcp_f32_e32 v91, v9
	v_rcp_f32_e32 v92, v10
	v_rcp_f32_e32 v93, v11
	s_waitcnt lgkmcnt(0)
	v_rcp_f32_e32 v96, v96
	v_rcp_f32_e32 v97, v97
	v_rcp_f32_e32 v94, v98
	v_rcp_f32_e32 v95, v99
	v_lshl_add_u32 v3, v190, 2, s0
	s_barrier
	s_cbranch_scc1 .LBB0_601
	v_mul_f32_e32 v8, v66, v12
	v_mul_f32_e32 v9, v50, v12
	ds_write2st64_b32 v3, v8, v9 offset1:1
	v_mul_f32_e32 v8, v34, v12
	v_mul_f32_e32 v9, v18, v12
	ds_write2st64_b32 v3, v8, v9 offset0:2 offset1:3
	v_mul_f32_e32 v8, v67, v13
	v_mul_f32_e32 v9, v51, v13
	ds_write2st64_b32 v3, v8, v9 offset0:4 offset1:5
	v_mul_f32_e32 v8, v35, v13
	v_mul_f32_e32 v9, v19, v13
	ds_write2st64_b32 v3, v8, v9 offset0:6 offset1:7
	v_mul_f32_e32 v8, v68, v16
	v_mul_f32_e32 v9, v52, v16
	ds_write2st64_b32 v3, v8, v9 offset0:8 offset1:9
	v_mul_f32_e32 v8, v36, v16
	v_mul_f32_e32 v9, v20, v16
	ds_write2st64_b32 v3, v8, v9 offset0:10 offset1:11
	v_mul_f32_e32 v8, v69, v17
	v_mul_f32_e32 v9, v53, v17
	ds_write2st64_b32 v3, v8, v9 offset0:12 offset1:13
	v_mul_f32_e32 v8, v37, v17
	v_mul_f32_e32 v9, v21, v17
	ds_write2st64_b32 v3, v8, v9 offset0:14 offset1:15
	v_mul_f32_e32 v8, v70, v84
	v_mul_f32_e32 v9, v54, v84
	ds_write2st64_b32 v3, v8, v9 offset0:16 offset1:17
	v_mul_f32_e32 v8, v38, v84
	v_mul_f32_e32 v9, v22, v84
	ds_write2st64_b32 v3, v8, v9 offset0:18 offset1:19
	v_mul_f32_e32 v8, v71, v85
	v_mul_f32_e32 v9, v55, v85
	ds_write2st64_b32 v3, v8, v9 offset0:20 offset1:21
	v_mul_f32_e32 v8, v39, v85
	v_mul_f32_e32 v9, v23, v85
	ds_write2st64_b32 v3, v8, v9 offset0:22 offset1:23
	v_mul_f32_e32 v8, v72, v88
	v_mul_f32_e32 v9, v56, v88
	ds_write2st64_b32 v3, v8, v9 offset0:24 offset1:25
	v_mul_f32_e32 v8, v40, v88
	v_mul_f32_e32 v9, v24, v88
	ds_write2st64_b32 v3, v8, v9 offset0:26 offset1:27
	v_mul_f32_e32 v8, v73, v89
	v_mul_f32_e32 v9, v57, v89
	ds_write2st64_b32 v3, v8, v9 offset0:28 offset1:29
	v_mul_f32_e32 v8, v41, v89
	v_mul_f32_e32 v9, v25, v89
	ds_write2st64_b32 v3, v8, v9 offset0:30 offset1:31
	v_mul_f32_e32 v8, v74, v90
	v_mul_f32_e32 v9, v58, v90
	ds_write2st64_b32 v3, v8, v9 offset0:32 offset1:33
	v_mul_f32_e32 v8, v42, v90
	v_mul_f32_e32 v9, v26, v90
	ds_write2st64_b32 v3, v8, v9 offset0:34 offset1:35
	v_mul_f32_e32 v8, v75, v91
	v_mul_f32_e32 v9, v59, v91
	ds_write2st64_b32 v3, v8, v9 offset0:36 offset1:37
	v_mul_f32_e32 v8, v43, v91
	v_mul_f32_e32 v9, v27, v91
	ds_write2st64_b32 v3, v8, v9 offset0:38 offset1:39
	v_mul_f32_e32 v8, v76, v92
	v_mul_f32_e32 v9, v60, v92
	ds_write2st64_b32 v3, v8, v9 offset0:40 offset1:41
	v_mul_f32_e32 v8, v44, v92
	v_mul_f32_e32 v9, v28, v92
	ds_write2st64_b32 v3, v8, v9 offset0:42 offset1:43
	v_mul_f32_e32 v8, v77, v93
	v_mul_f32_e32 v9, v61, v93
	ds_write2st64_b32 v3, v8, v9 offset0:44 offset1:45
	v_mul_f32_e32 v8, v45, v93
	v_mul_f32_e32 v9, v29, v93
	ds_write2st64_b32 v3, v8, v9 offset0:46 offset1:47
	v_mul_f32_e32 v8, v78, v96
	v_mul_f32_e32 v9, v62, v96
	ds_write2st64_b32 v3, v8, v9 offset0:48 offset1:49
	v_mul_f32_e32 v8, v46, v96
	v_mul_f32_e32 v9, v30, v96
	ds_write2st64_b32 v3, v8, v9 offset0:50 offset1:51
	v_mul_f32_e32 v8, v79, v97
	v_mul_f32_e32 v9, v63, v97
	ds_write2st64_b32 v3, v8, v9 offset0:52 offset1:53
	v_mul_f32_e32 v8, v47, v97
	v_mul_f32_e32 v9, v31, v97
	ds_write2st64_b32 v3, v8, v9 offset0:54 offset1:55
	v_mul_f32_e32 v8, v80, v94
	v_mul_f32_e32 v9, v64, v94
	ds_write2st64_b32 v3, v8, v9 offset0:56 offset1:57
	v_mul_f32_e32 v8, v48, v94
	v_mul_f32_e32 v9, v32, v94
	ds_write2st64_b32 v3, v8, v9 offset0:58 offset1:59
	v_mul_f32_e32 v8, v81, v95
	v_mul_f32_e32 v9, v65, v95
	ds_write2st64_b32 v3, v8, v9 offset0:60 offset1:61
	v_mul_f32_e32 v8, v49, v95
	v_mul_f32_e32 v9, v33, v95
	ds_write2st64_b32 v3, v8, v9 offset0:62 offset1:63
